# final RMSNorm: the eight gain vectors loaded once before the row loop instead of reloaded (each with a full vmcnt(0) wait) inside it
# speedup vs baseline: 1.0015x; 1.0015x over previous
.LBB0_989:
	s_cmp_lt_i32 s90, 26
	s_cselect_b64 s[0:1], -1, 0
	s_cmp_gt_i32 s91, 25
	s_cselect_b64 s[2:3], -1, 0
	s_and_b64 s[0:1], s[0:1], s[2:3]
	s_and_b64 vcc, exec, s[0:1]
	s_cbranch_vccz .LBB0_995
	v_readlane_b32 s0, v250, 2
	v_readlane_b32 s1, v250, 3
	s_mov_b32 s2, s0
	s_lshl_b32 s0, s0, 11
	s_and_b32 s0, s0, 0x3800
	s_and_b32 s1, s2, -8
	s_add_i32 s0, s0, s1
	v_readlane_b32 s1, v253, 51
	s_add_i32 s2, s0, s1
	v_readlane_b32 s0, v250, 26
	v_readlane_b32 s1, v250, 27
	v_mov_b32_e32 v0, 0
	s_and_b64 s[0:1], s[0:1], exec
	v_readlane_b32 s0, v250, 24
	v_mbcnt_lo_u32_b32 v0, -1, v0
	s_cselect_b32 s0, s2, s0
	s_waitcnt lgkmcnt(0)
	v_mov_b32_e32 v1, 0
	v_mbcnt_hi_u32_b32 v4, -1, v0
	s_cmpk_gt_i32 s0, 0x3fff
	s_cbranch_scc1 .LBB0_995
	v_readlane_b32 s2, v250, 26
	v_readlane_b32 s3, v250, 27
	v_ashrrev_i32_e32 v5, 31, v4
	s_and_b64 s[2:3], s[2:3], exec
	v_lshlrev_b64 v[14:15], 4, v[4:5]
	v_ashrrev_i32_e32 v2, 4, v4
	v_bfe_u32 v36, v4, 3, 1
	v_lshlrev_b32_e32 v0, 3, v4
	v_lshl_add_u64 v[4:5], s[84:85], 0, v[14:15]
	s_mov_b64 s[2:3], 0x1000
	v_readlane_b32 s1, v250, 38
	v_lshl_add_u64 v[6:7], v[4:5], 0, s[2:3]
	s_mov_b64 s[2:3], 0x1400
	s_cselect_b32 s4, 0x100, s1
	v_ashrrev_i32_e32 v3, 31, v2
	s_add_u32 s5, s88, 0x200000
	v_lshl_add_u64 v[8:9], v[4:5], 0, s[2:3]
	s_mov_b64 s[2:3], 0x1800
	s_flbit_i32_b32 s1, 0
	v_lshlrev_b64 v[2:3], 14, v[2:3]
	s_addc_u32 s6, s89, 0
	v_lshl_add_u64 v[10:11], v[4:5], 0, s[2:3]
	s_mov_b64 s[2:3], 0x1c00
	s_min_u32 s10, s1, 32
	v_lshl_add_u64 v[2:3], s[46:47], 0, v[2:3]
	v_and_b32_e32 v37, 56, v0
	v_lshl_add_u64 v[12:13], v[4:5], 0, s[2:3]
	v_lshl_add_u64 v[14:15], s[86:87], 0, v[14:15]
	s_lshl_b32 s7, s4, 1
	s_lshl_b32 s8, s0, 6
	s_lshl_b32 s9, s4, 7
	s_mov_b32 s19, 0
	s_sub_i32 s11, 32, s10
	s_mov_b32 s12, 0x10000
	s_mov_b32 s13, 0x20000
	s_mov_b32 s14, 0x30000
	s_mov_b32 s15, 0x40000
	s_mov_b32 s16, 0x50000
	s_mov_b32 s17, 0x60000
	s_mov_b32 s18, 0x70000
	v_mov_b32_e32 v38, 0x3727c5ac
	s_movk_i32 s20, 0x1000
	global_load_dwordx4 v[104:107], v[4:5], off
	global_load_dwordx4 v[108:111], v[4:5], off offset:1024
	global_load_dwordx4 v[112:115], v[4:5], off offset:2048
	global_load_dwordx4 v[116:119], v[4:5], off offset:3072
	global_load_dwordx4 v[120:123], v[6:7], off
	global_load_dwordx4 v[124:127], v[8:9], off
	global_load_dwordx4 v[128:131], v[10:11], off
	global_load_dwordx4 v[132:135], v[12:13], off
	s_waitcnt vmcnt(0)
	s_branch .LBB0_993

.LBB0_993:
	s_add_i32 s2, s4, s0
	s_cmpk_lt_i32 s2, 0x4000
	s_cselect_b32 s22, s2, s0
	s_ashr_i32 s24, s22, 7
	s_lshl_b32 s1, s22, 6
	s_ashr_i32 s25, s24, 31
	s_and_b32 s21, s1, 0x3c0
	s_lshl_b32 s1, s22, 2
	s_ashr_i32 s23, s22, 31
	s_lshl_b64 s[24:25], s[24:25], 19
	s_lshr_b32 s3, s22, 3
	s_and_b32 s28, s1, 32
	s_lshl_b64 s[22:23], s[22:23], 3
	s_add_u32 s22, s5, s22
	s_addc_u32 s23, s6, s23
	s_ashr_i32 s1, s0, 31
	s_lshl_b64 s[26:27], s[0:1], 3
	s_add_u32 s26, s5, s26
	s_addc_u32 s27, s6, s27
	global_load_dwordx2 v[16:17], v1, s[26:27]
	global_load_dwordx2 v[24:25], v1, s[22:23]
	v_and_or_b32 v0, s3, 14, v36
	s_lshr_b32 s26, s0, 3
	v_lshlrev_b32_e32 v27, 10, v0
	v_lshl_add_u64 v[18:19], v[2:3], 0, s[24:25]
	s_ashr_i32 s24, s0, 7
	v_and_or_b32 v0, s26, 14, v36
	v_or_b32_e32 v26, s21, v37
	s_and_b32 s3, s8, 0x3c0
	s_lshr_b32 s21, s8, 4
	s_ashr_i32 s25, s24, 31
	v_lshlrev_b32_e32 v29, 10, v0
	s_and_b32 s21, s21, 32
	v_or_b32_e32 v28, s3, v37
	s_lshl_b64 s[22:23], s[24:25], 19
	v_lshl_add_u64 v[20:21], v[2:3], 0, s[22:23]
	s_lshl_b64 s[22:23], s[0:1], 13
	s_waitcnt vmcnt(6)
	v_lshl_add_u64 v[54:55], v[14:15], 0, s[22:23]
	s_cmpk_gt_i32 s2, 0x3fff
	s_waitcnt vmcnt(1)
	v_mov_b32_e32 v0, v17
	v_lshlrev_b64 v[22:23], s10, v[0:1]
	v_bitop3_b32 v0, v26, v27, s28 bitop3:0xde
	v_lshl_add_u64 v[44:45], v[18:19], 0, v[0:1]
	v_bitop3_b32 v0, v28, v29, s21 bitop3:0xde
	v_lshl_add_u64 v[46:47], v[20:21], 0, v[0:1]
	v_add_co_u32_e32 v18, vcc, s17, v46
	v_cvt_f32_u32_e32 v0, v16
	s_nop 0
	v_addc_co_u32_e32 v19, vcc, 0, v47, vcc
	v_add_co_u32_e32 v20, vcc, s16, v46
	v_min_u32_e32 v16, 1, v22
	s_nop 0
	v_addc_co_u32_e32 v21, vcc, 0, v47, vcc
	global_load_dwordx2 v[34:35], v[18:19], off
	global_load_dwordx2 v[48:49], v[20:21], off
	global_load_dwordx2 v[50:51], v[46:47], off
	v_add_co_u32_e32 v18, vcc, s18, v46
	v_or_b32_e32 v39, v23, v16
	s_nop 0
	v_addc_co_u32_e32 v19, vcc, 0, v47, vcc
	v_add_co_u32_e32 v56, vcc, s12, v44
	v_cvt_f32_u32_e32 v39, v39
	s_nop 0
	v_addc_co_u32_e32 v57, vcc, 0, v45, vcc
	v_add_co_u32_e32 v58, vcc, s13, v44
	global_load_dwordx2 v[52:53], v[18:19], off
	s_nop 0
	v_addc_co_u32_e32 v59, vcc, 0, v45, vcc
	v_add_co_u32_e32 v60, vcc, s14, v44
	v_ldexp_f32 v39, v39, s11
	s_nop 0
	v_addc_co_u32_e32 v61, vcc, 0, v45, vcc
	v_add_co_u32_e32 v62, vcc, s15, v44
	v_fmac_f32_e32 v0, 0x4f800000, v39
	s_nop 0
	v_addc_co_u32_e32 v63, vcc, 0, v45, vcc
	v_add_co_u32_e32 v64, vcc, s16, v44
	v_fmamk_f32 v0, v0, 0x30000000, v38
	s_nop 0
	v_addc_co_u32_e32 v65, vcc, 0, v45, vcc
	v_add_co_u32_e32 v66, vcc, s17, v44
	v_rsq_f32_e32 v0, v0
	s_nop 0
	v_addc_co_u32_e32 v67, vcc, 0, v45, vcc
	v_add_co_u32_e32 v68, vcc, s18, v44
	s_nop 1
	v_addc_co_u32_e32 v69, vcc, 0, v45, vcc
	global_load_dwordx2 v[32:33], v[44:45], off
	global_load_dwordx2 v[30:31], v[56:57], off
	global_load_dwordx2 v[28:29], v[58:59], off
	global_load_dwordx2 v[26:27], v[60:61], off
	global_load_dwordx2 v[22:23], v[62:63], off
	global_load_dwordx2 v[20:21], v[64:65], off
	global_load_dwordx2 v[18:19], v[66:67], off
	global_load_dwordx2 v[16:17], v[68:69], off
	v_add_co_u32_e32 v44, vcc, s15, v46
	s_nop 1
	v_addc_co_u32_e32 v45, vcc, 0, v47, vcc
	v_add_co_u32_e32 v56, vcc, s14, v46
	s_nop 1
	v_addc_co_u32_e32 v57, vcc, 0, v47, vcc
	v_add_co_u32_e32 v58, vcc, s13, v46
	s_nop 1
	v_addc_co_u32_e32 v59, vcc, 0, v47, vcc
	v_add_co_u32_e32 v46, vcc, s12, v46
	s_nop 1
	v_addc_co_u32_e32 v47, vcc, 0, v47, vcc
	global_load_dwordx2 v[60:61], v[44:45], off
	global_load_dwordx2 v[62:63], v[56:57], off
	global_load_dwordx2 v[64:65], v[58:59], off
	global_load_dwordx2 v[66:67], v[46:47], off
	s_waitcnt vmcnt(0)
	v_lshlrev_b32_e32 v44, 16, v50
	v_and_b32_e32 v45, 0xffff0000, v50
	v_lshlrev_b32_e32 v46, 16, v51
	v_and_b32_e32 v47, 0xffff0000, v51
	v_pk_mul_f32 v[44:45], v[0:1], v[44:45] op_sel_hi:[0,1]
	v_pk_mul_f32 v[46:47], v[0:1], v[46:47] op_sel_hi:[0,1]
	v_pk_mul_f32 v[42:43], v[106:107], v[46:47]
	v_pk_mul_f32 v[40:41], v[104:105], v[44:45]
	global_store_dwordx4 v[54:55], v[40:43], off
	v_lshlrev_b32_e32 v50, 16, v61
	v_and_b32_e32 v51, 0xffff0000, v61
	v_pk_mul_f32 v[50:51], v[0:1], v[50:51] op_sel_hi:[0,1]
	v_lshlrev_b32_e32 v44, 16, v66
	v_and_b32_e32 v45, 0xffff0000, v66
	v_lshlrev_b32_e32 v46, 16, v67
	v_and_b32_e32 v47, 0xffff0000, v67
	v_pk_mul_f32 v[46:47], v[0:1], v[46:47] op_sel_hi:[0,1]
	v_pk_mul_f32 v[44:45], v[0:1], v[44:45] op_sel_hi:[0,1]
	v_pk_mul_f32 v[40:41], v[108:109], v[44:45]
	v_pk_mul_f32 v[42:43], v[110:111], v[46:47]
	global_store_dwordx4 v[54:55], v[40:43], off offset:1024
	v_lshlrev_b32_e32 v44, 16, v64
	v_and_b32_e32 v45, 0xffff0000, v64
	v_lshlrev_b32_e32 v46, 16, v65
	v_and_b32_e32 v47, 0xffff0000, v65
	v_pk_mul_f32 v[46:47], v[0:1], v[46:47] op_sel_hi:[0,1]
	v_pk_mul_f32 v[44:45], v[0:1], v[44:45] op_sel_hi:[0,1]
	v_pk_mul_f32 v[40:41], v[112:113], v[44:45]
	v_pk_mul_f32 v[42:43], v[114:115], v[46:47]
	global_store_dwordx4 v[54:55], v[40:43], off offset:2048
	v_lshlrev_b32_e32 v44, 16, v62
	v_and_b32_e32 v45, 0xffff0000, v62
	v_lshlrev_b32_e32 v46, 16, v63
	v_and_b32_e32 v47, 0xffff0000, v63
	v_pk_mul_f32 v[46:47], v[0:1], v[46:47] op_sel_hi:[0,1]
	v_pk_mul_f32 v[44:45], v[0:1], v[44:45] op_sel_hi:[0,1]
	v_pk_mul_f32 v[40:41], v[116:117], v[44:45]
	v_pk_mul_f32 v[42:43], v[118:119], v[46:47]
	global_store_dwordx4 v[54:55], v[40:43], off offset:3072
	v_lshlrev_b32_e32 v46, 16, v60
	v_and_b32_e32 v47, 0xffff0000, v60
	v_add_co_u32_e32 v44, vcc, s20, v54
	v_pk_mul_f32 v[46:47], v[0:1], v[46:47] op_sel_hi:[0,1]
	s_nop 0
	v_addc_co_u32_e32 v45, vcc, 0, v55, vcc
	v_pk_mul_f32 v[40:41], v[120:121], v[46:47]
	v_pk_mul_f32 v[42:43], v[122:123], v[50:51]
	global_store_dwordx4 v[44:45], v[40:43], off
	v_lshlrev_b32_e32 v46, 16, v48
	v_and_b32_e32 v47, 0xffff0000, v48
	v_lshlrev_b32_e32 v48, 16, v49
	v_and_b32_e32 v49, 0xffff0000, v49
	v_pk_mul_f32 v[48:49], v[0:1], v[48:49] op_sel_hi:[0,1]
	v_pk_mul_f32 v[46:47], v[0:1], v[46:47] op_sel_hi:[0,1]
	v_pk_mul_f32 v[40:41], v[124:125], v[46:47]
	v_pk_mul_f32 v[42:43], v[126:127], v[48:49]
	global_store_dwordx4 v[44:45], v[40:43], off offset:1024
	v_lshlrev_b32_e32 v46, 16, v34
	v_and_b32_e32 v47, 0xffff0000, v34
	v_lshlrev_b32_e32 v34, 16, v35
	v_and_b32_e32 v35, 0xffff0000, v35
	v_pk_mul_f32 v[34:35], v[0:1], v[34:35] op_sel_hi:[0,1]
	v_pk_mul_f32 v[46:47], v[0:1], v[46:47] op_sel_hi:[0,1]
	v_pk_mul_f32 v[40:41], v[128:129], v[46:47]
	v_pk_mul_f32 v[42:43], v[130:131], v[34:35]
	global_store_dwordx4 v[44:45], v[40:43], off offset:2048
	v_lshlrev_b32_e32 v34, 16, v52
	v_and_b32_e32 v35, 0xffff0000, v52
	v_lshlrev_b32_e32 v46, 16, v53
	v_and_b32_e32 v47, 0xffff0000, v53
	v_pk_mul_f32 v[46:47], v[0:1], v[46:47] op_sel_hi:[0,1]
	v_pk_mul_f32 v[34:35], v[0:1], v[34:35] op_sel_hi:[0,1]
	v_pk_mul_f32 v[40:41], v[132:133], v[34:35]
	v_pk_mul_f32 v[42:43], v[134:135], v[46:47]
	global_store_dwordx4 v[44:45], v[40:43], off offset:3072
	s_cbranch_scc1 .LBB0_992
	v_mov_b32_e32 v0, v25
	v_cvt_f32_u32_e32 v34, v24
	v_lshlrev_b64 v[24:25], s10, v[0:1]
	v_min_u32_e32 v0, 1, v24
	v_or_b32_e32 v0, v25, v0
	v_cvt_f32_u32_e32 v0, v0
	s_ashr_i32 s3, s2, 31
	v_lshlrev_b32_e32 v24, 16, v32
	v_and_b32_e32 v25, 0xffff0000, v32
	v_ldexp_f32 v0, v0, s11
	v_fmac_f32_e32 v34, 0x4f800000, v0
	v_fmamk_f32 v0, v34, 0x30000000, v38
	v_rsq_f32_e32 v0, v0
	v_lshlrev_b32_e32 v32, 16, v33
	v_and_b32_e32 v33, 0xffff0000, v33
	s_lshl_b64 s[2:3], s[2:3], 13
	v_pk_mul_f32 v[24:25], v[0:1], v[24:25] op_sel_hi:[0,1]
	v_pk_mul_f32 v[32:33], v[0:1], v[32:33] op_sel_hi:[0,1]
	v_lshl_add_u64 v[44:45], v[14:15], 0, s[2:3]
	v_pk_mul_f32 v[34:35], v[106:107], v[32:33]
	v_pk_mul_f32 v[32:33], v[104:105], v[24:25]
	global_store_dwordx4 v[44:45], v[32:35], off
	v_lshlrev_b32_e32 v24, 16, v30
	v_and_b32_e32 v25, 0xffff0000, v30
	v_lshlrev_b32_e32 v30, 16, v31
	v_and_b32_e32 v31, 0xffff0000, v31
	v_pk_mul_f32 v[40:41], v[0:1], v[30:31] op_sel_hi:[0,1]
	v_pk_mul_f32 v[24:25], v[0:1], v[24:25] op_sel_hi:[0,1]
	v_pk_mul_f32 v[30:31], v[108:109], v[24:25]
	v_pk_mul_f32 v[32:33], v[110:111], v[40:41]
	global_store_dwordx4 v[44:45], v[30:33], off offset:1024
	v_lshlrev_b32_e32 v24, 16, v28
	v_and_b32_e32 v25, 0xffff0000, v28
	v_lshlrev_b32_e32 v28, 16, v29
	v_and_b32_e32 v29, 0xffff0000, v29
	v_pk_mul_f32 v[34:35], v[0:1], v[28:29] op_sel_hi:[0,1]
	v_pk_mul_f32 v[24:25], v[0:1], v[24:25] op_sel_hi:[0,1]
	v_pk_mul_f32 v[28:29], v[112:113], v[24:25]
	v_pk_mul_f32 v[30:31], v[114:115], v[34:35]
	global_store_dwordx4 v[44:45], v[28:31], off offset:2048
	v_lshlrev_b32_e32 v24, 16, v26
	v_and_b32_e32 v25, 0xffff0000, v26
	v_lshlrev_b32_e32 v26, 16, v27
	v_and_b32_e32 v27, 0xffff0000, v27
	v_pk_mul_f32 v[26:27], v[0:1], v[26:27] op_sel_hi:[0,1]
	v_pk_mul_f32 v[24:25], v[0:1], v[24:25] op_sel_hi:[0,1]
	v_pk_mul_f32 v[24:25], v[116:117], v[24:25]
	v_pk_mul_f32 v[26:27], v[118:119], v[26:27]
	global_store_dwordx4 v[44:45], v[24:27], off offset:3072
	v_lshlrev_b32_e32 v28, 16, v22
	v_and_b32_e32 v29, 0xffff0000, v22
	v_lshlrev_b32_e32 v22, 16, v23
	v_and_b32_e32 v23, 0xffff0000, v23
	v_add_co_u32_e32 v30, vcc, s20, v44
	v_pk_mul_f32 v[32:33], v[0:1], v[22:23] op_sel_hi:[0,1]
	v_pk_mul_f32 v[22:23], v[0:1], v[28:29] op_sel_hi:[0,1]
	v_addc_co_u32_e32 v31, vcc, 0, v45, vcc
	v_pk_mul_f32 v[22:23], v[120:121], v[22:23]
	v_pk_mul_f32 v[24:25], v[122:123], v[32:33]
	global_store_dwordx4 v[30:31], v[22:25], off
	v_lshlrev_b32_e32 v26, 16, v20
	v_and_b32_e32 v27, 0xffff0000, v20
	v_lshlrev_b32_e32 v20, 16, v21
	v_and_b32_e32 v21, 0xffff0000, v21
	v_pk_mul_f32 v[28:29], v[0:1], v[20:21] op_sel_hi:[0,1]
	v_pk_mul_f32 v[20:21], v[0:1], v[26:27] op_sel_hi:[0,1]
	v_pk_mul_f32 v[20:21], v[124:125], v[20:21]
	v_pk_mul_f32 v[22:23], v[126:127], v[28:29]
	global_store_dwordx4 v[30:31], v[20:23], off offset:1024
	v_lshlrev_b32_e32 v24, 16, v18
	v_and_b32_e32 v25, 0xffff0000, v18
	v_lshlrev_b32_e32 v18, 16, v19
	v_and_b32_e32 v19, 0xffff0000, v19
	v_pk_mul_f32 v[26:27], v[0:1], v[18:19] op_sel_hi:[0,1]
	v_pk_mul_f32 v[18:19], v[0:1], v[24:25] op_sel_hi:[0,1]
	v_pk_mul_f32 v[18:19], v[128:129], v[18:19]
	v_pk_mul_f32 v[20:21], v[130:131], v[26:27]
	global_store_dwordx4 v[30:31], v[18:21], off offset:2048
	v_lshlrev_b32_e32 v22, 16, v16
	v_and_b32_e32 v23, 0xffff0000, v16
	v_lshlrev_b32_e32 v16, 16, v17
	v_and_b32_e32 v17, 0xffff0000, v17
	v_pk_mul_f32 v[24:25], v[0:1], v[16:17] op_sel_hi:[0,1]
	v_pk_mul_f32 v[16:17], v[0:1], v[22:23] op_sel_hi:[0,1]
	v_pk_mul_f32 v[16:17], v[132:133], v[16:17]
	v_pk_mul_f32 v[18:19], v[134:135], v[24:25]
	global_store_dwordx4 v[30:31], v[16:19], off offset:3072
	s_branch .LBB0_992
